# merge GEMM (hm3): branch accumulator re-zeroing after each fold replaced by C=0 first-touch MFMAs on the K-tile that follows a fold (64 v_mov per fold removed)
# baseline (speedup 1.0000x reference)
.LBB0_996:
.LBB0_997:
	s_add_i32 s16, s58, 0xc000
	s_cmp_lg_u32 s58, 0x18000
	s_cselect_b32 s58, s16, 0
	s_add_i32 s16, s57, 0xc000
	s_cmp_lg_u32 s57, 0x18000
	s_cselect_b32 s57, s16, 0
	s_add_i32 s65, s65, 1
	s_cmp_eq_u32 s65, 32
	s_cbranch_scc1 .LBB0_1037

.LBB0_1002:
	s_waitcnt lgkmcnt(0)
	s_barrier
	s_cmp_eq_u32 s22, 0
	s_cbranch_scc1 .Lhm3_zc
	v_mfma_f32_16x16x32_bf16 v[126:129], v[146:149], v[186:189], v[126:129]
	v_mfma_f32_16x16x32_bf16 v[122:125], v[154:157], v[186:189], v[122:125]
	v_mfma_f32_16x16x32_bf16 v[110:113], v[146:149], v[178:181], v[110:113]
	v_mfma_f32_16x16x32_bf16 v[106:109], v[154:157], v[178:181], v[106:109]
	v_mfma_f32_16x16x32_bf16 v[94:97], v[146:149], v[170:173], v[94:97]
	v_mfma_f32_16x16x32_bf16 v[90:93], v[154:157], v[170:173], v[90:93]
	v_mfma_f32_16x16x32_bf16 v[78:81], v[146:149], v[162:165], v[78:81]
	v_mfma_f32_16x16x32_bf16 v[74:77], v[154:157], v[162:165], v[74:77]
	v_mfma_f32_16x16x32_bf16 v[126:129], v[150:153], v[190:193], v[126:129]
	v_mfma_f32_16x16x32_bf16 v[122:125], v[158:161], v[190:193], v[122:125]
	v_mfma_f32_16x16x32_bf16 v[110:113], v[150:153], v[182:185], v[110:113]
	v_mfma_f32_16x16x32_bf16 v[106:109], v[158:161], v[182:185], v[106:109]
	v_mfma_f32_16x16x32_bf16 v[94:97], v[150:153], v[174:177], v[94:97]
	v_mfma_f32_16x16x32_bf16 v[90:93], v[158:161], v[174:177], v[90:93]
	v_mfma_f32_16x16x32_bf16 v[78:81], v[150:153], v[166:169], v[78:81]
	v_mfma_f32_16x16x32_bf16 v[74:77], v[158:161], v[166:169], v[74:77]
	v_mfma_f32_16x16x32_bf16 v[118:121], v[130:133], v[186:189], v[118:121]
	v_mfma_f32_16x16x32_bf16 v[114:117], v[138:141], v[186:189], v[114:117]
	v_mfma_f32_16x16x32_bf16 v[102:105], v[130:133], v[178:181], v[102:105]
	v_mfma_f32_16x16x32_bf16 v[98:101], v[138:141], v[178:181], v[98:101]
	v_mfma_f32_16x16x32_bf16 v[86:89], v[130:133], v[170:173], v[86:89]
	v_mfma_f32_16x16x32_bf16 v[82:85], v[138:141], v[170:173], v[82:85]
	v_mfma_f32_16x16x32_bf16 v[70:73], v[130:133], v[162:165], v[70:73]
	v_mfma_f32_16x16x32_bf16 v[66:69], v[138:141], v[162:165], v[66:69]
	v_mfma_f32_16x16x32_bf16 v[118:121], v[134:137], v[190:193], v[118:121]
	v_mfma_f32_16x16x32_bf16 v[114:117], v[142:145], v[190:193], v[114:117]
	v_mfma_f32_16x16x32_bf16 v[102:105], v[134:137], v[182:185], v[102:105]
	v_mfma_f32_16x16x32_bf16 v[98:101], v[142:145], v[182:185], v[98:101]
	v_mfma_f32_16x16x32_bf16 v[86:89], v[134:137], v[174:177], v[86:89]
	v_mfma_f32_16x16x32_bf16 v[82:85], v[142:145], v[174:177], v[82:85]
	v_mfma_f32_16x16x32_bf16 v[70:73], v[134:137], v[166:169], v[70:73]
	v_mfma_f32_16x16x32_bf16 v[66:69], v[142:145], v[166:169], v[66:69]
.Lhm3_join:
	s_barrier
	s_cmp_lg_u32 s22, 7
	s_cbranch_scc1 .LBB0_997
	s_cmp_gt_u32 s65, 7
	s_waitcnt vmcnt(6)
	v_cvt_f32_ubyte3_e32 v131, v206
	v_cvt_f32_ubyte2_e32 v130, v206
	v_cvt_f32_ubyte1_e32 v133, v206
	v_cvt_f32_ubyte0_e32 v132, v206
	s_cselect_b64 s[16:17], -1, 0
	v_pk_mul_f32 v[134:135], v[132:133], s[20:21] op_sel_hi:[1,0]
	v_pk_mul_f32 v[136:137], v[130:131], s[20:21] op_sel_hi:[1,0]
	v_cvt_f32_ubyte1_e32 v133, v207
	v_cvt_f32_ubyte0_e32 v132, v207
	v_cvt_f32_ubyte3_e32 v131, v207
	v_cvt_f32_ubyte2_e32 v130, v207
	v_pk_mul_f32 v[130:131], v[130:131], s[20:21] op_sel_hi:[1,0]
	v_pk_mul_f32 v[132:133], v[132:133], s[20:21] op_sel_hi:[1,0]
	v_pk_mul_f32 v[128:129], v[136:137], v[128:129]
	v_pk_mul_f32 v[126:127], v[134:135], v[126:127]
	s_mov_b64 s[22:23], -1
	s_and_b64 vcc, exec, s[16:17]
	s_cbranch_vccz .LBB0_1005
	v_pk_add_f32 v[64:65], v[64:65], v[128:129]
	v_pk_add_f32 v[62:63], v[62:63], v[126:127]
	v_pk_fma_f32 v[60:61], v[130:131], v[124:125], v[60:61]
	v_pk_fma_f32 v[58:59], v[132:133], v[122:123], v[58:59]
	s_mov_b64 s[22:23], 0

.Lhm3_zc:
	v_mfma_f32_16x16x32_bf16 v[126:129], v[146:149], v[186:189], 0
	v_mfma_f32_16x16x32_bf16 v[122:125], v[154:157], v[186:189], 0
	v_mfma_f32_16x16x32_bf16 v[110:113], v[146:149], v[178:181], 0
	v_mfma_f32_16x16x32_bf16 v[106:109], v[154:157], v[178:181], 0
	v_mfma_f32_16x16x32_bf16 v[94:97], v[146:149], v[170:173], 0
	v_mfma_f32_16x16x32_bf16 v[90:93], v[154:157], v[170:173], 0
	v_mfma_f32_16x16x32_bf16 v[78:81], v[146:149], v[162:165], 0
	v_mfma_f32_16x16x32_bf16 v[74:77], v[154:157], v[162:165], 0
	v_mfma_f32_16x16x32_bf16 v[126:129], v[150:153], v[190:193], v[126:129]
	v_mfma_f32_16x16x32_bf16 v[122:125], v[158:161], v[190:193], v[122:125]
	v_mfma_f32_16x16x32_bf16 v[110:113], v[150:153], v[182:185], v[110:113]
	v_mfma_f32_16x16x32_bf16 v[106:109], v[158:161], v[182:185], v[106:109]
	v_mfma_f32_16x16x32_bf16 v[94:97], v[150:153], v[174:177], v[94:97]
	v_mfma_f32_16x16x32_bf16 v[90:93], v[158:161], v[174:177], v[90:93]
	v_mfma_f32_16x16x32_bf16 v[78:81], v[150:153], v[166:169], v[78:81]
	v_mfma_f32_16x16x32_bf16 v[74:77], v[158:161], v[166:169], v[74:77]
	v_mfma_f32_16x16x32_bf16 v[118:121], v[130:133], v[186:189], 0
	v_mfma_f32_16x16x32_bf16 v[114:117], v[138:141], v[186:189], 0
	v_mfma_f32_16x16x32_bf16 v[102:105], v[130:133], v[178:181], 0
	v_mfma_f32_16x16x32_bf16 v[98:101], v[138:141], v[178:181], 0
	v_mfma_f32_16x16x32_bf16 v[86:89], v[130:133], v[170:173], 0
	v_mfma_f32_16x16x32_bf16 v[82:85], v[138:141], v[170:173], 0
	v_mfma_f32_16x16x32_bf16 v[70:73], v[130:133], v[162:165], 0
	v_mfma_f32_16x16x32_bf16 v[66:69], v[138:141], v[162:165], 0
	v_mfma_f32_16x16x32_bf16 v[118:121], v[134:137], v[190:193], v[118:121]
	v_mfma_f32_16x16x32_bf16 v[114:117], v[142:145], v[190:193], v[114:117]
	v_mfma_f32_16x16x32_bf16 v[102:105], v[134:137], v[182:185], v[102:105]
	v_mfma_f32_16x16x32_bf16 v[98:101], v[142:145], v[182:185], v[98:101]
	v_mfma_f32_16x16x32_bf16 v[86:89], v[134:137], v[174:177], v[86:89]
	v_mfma_f32_16x16x32_bf16 v[82:85], v[142:145], v[174:177], v[82:85]
	v_mfma_f32_16x16x32_bf16 v[70:73], v[134:137], v[166:169], v[70:73]
	v_mfma_f32_16x16x32_bf16 v[66:69], v[142:145], v[166:169], v[66:69]
	s_branch .Lhm3_join
